# MLA attention loop: row-sum via 16x16x32 MFMA (half the matrix-pipe time of the 32x32x16 P x ones form) and 8 of 16 first-half exps moved from the inter-barrier segment into the P.V MFMA gaps
# speedup vs baseline: 1.0056x; 1.0056x over previous
; #define SBAR() __builtin_amdgcn_sched_barrier(0)
; #define SLOAD(i, k0) do { st_[i].vs = *reinterpret_cast<const bf16x8*>(&Vh[(size_t)((k0) + sr) * LDK + sc]); \
;     st_[i].ks = *reinterpret_cast<const bf16x8*>(&Kh[(size_t)((k0) + sr) * LDK + sc]); \
;     if (DQ == 96) st_[i].kr = *reinterpret_cast<const bf16x8*>(&Kr[(size_t)((k0) + sr2) * 32 + sc2]); } while (0)
; #define SLOAD(i, k0) do { st_[i].vs = *reinterpret_cast<const bf16x8*>(&Vh[(size_t)((k0) + sr) * LDK + sc]); \
;     st_[i].ks = *reinterpret_cast<const bf16x8*>(&Kh[(size_t)((k0) + sr) * LDK + sc]); \
;     if (DQ == 96) st_[i].kr = *reinterpret_cast<const bf16x8*>(&Kr[(size_t)((k0) + sr2) * 32 + sc2]); } while (0)
; template <int DQ>
; __device__ __forceinline__ void qkt(f32x16& p0, f32x16& p1, const char* Ks, const bf16x8* qr, const f32x16& ci, int r32, int hi) {
;     constexpr int KROW = ACfg<DQ>::KROW;
; #pragma unroll
;     for (int d0 = 0; d0 < ACfg<DQ>::ND; ++d0) { const int cb = (d0 * 16 + hi * 8) * 2;
;         bf16x8 b0 = *reinterpret_cast<const bf16x8*>(Ks + r32 * KROW + cb);
;         bf16x8 b1 = *reinterpret_cast<const bf16x8*>(Ks + (32 + r32) * KROW + cb);
;         p0 = __builtin_amdgcn_mfma_f32_32x32x16_bf16(b0, qr[d0], d0 == 0 ? ci : p0, 0, 0, 0);
;         p1 = __builtin_amdgcn_mfma_f32_32x32x16_bf16(b1, qr[d0], d0 == 0 ? ci : p1, 0, 0, 0); }
; }
; template <int DQ, bool WIN, int LDQ, int LDK> ...
;     ...
;         SBAR(); qkt<DQ>(pA0, pA1, K_lds, qr, minit, r32, hi);
;         finish(pB0, pB1); SBAR();
;         if (j + 3 < NT) SLOAD(SE, KBASE(j + 3)); SBAR();
;         pv(vb0 + SHM_V);
.LBB0_1094:
	ds_read_b128 v[198:201], v191 offset:36352
	ds_read_b128 v[80:83], v191 offset:29696
	ds_read_b128 v[202:205], v191 offset:29728
	v_exp_f32_e32 v72, v72
	v_exp_f32_e32 v73, v73
	v_exp_f32_e32 v74, v74
	s_waitcnt lgkmcnt(1)
	v_mfma_f32_32x32x16_bf16 v[96:111], v[80:83], v[134:137], v[48:63]
	v_exp_f32_e32 v75, v75
	v_exp_f32_e32 v197, v64
	v_exp_f32_e32 v206, v77
	v_exp_f32_e32 v207, v78
	v_exp_f32_e32 v208, v79
	v_mfma_f32_32x32x16_bf16 v[80:95], v[198:201], v[134:137], v[48:63]
	ds_read_b128 v[198:201], v191 offset:36384
	s_waitcnt lgkmcnt(1)
	v_mfma_f32_32x32x16_bf16 v[96:111], v[202:205], v[130:133], v[96:111]
	s_waitcnt lgkmcnt(0)
	v_mfma_f32_32x32x16_bf16 v[80:95], v[198:201], v[130:133], v[80:95]
	ds_read_b128 v[198:201], v191 offset:29760
	ds_read_b128 v[202:205], v191 offset:36416
	s_waitcnt lgkmcnt(1)
	v_mfma_f32_32x32x16_bf16 v[96:111], v[198:201], v[126:129], v[96:111]
	s_waitcnt lgkmcnt(0)
	v_mfma_f32_32x32x16_bf16 v[80:95], v[202:205], v[126:129], v[80:95]
	ds_read_b128 v[198:201], v191 offset:29792
	ds_read_b128 v[202:205], v191 offset:36448
	s_waitcnt lgkmcnt(1)
	v_mfma_f32_32x32x16_bf16 v[96:111], v[198:201], v[122:125], v[96:111]
	s_waitcnt lgkmcnt(0)
	v_mfma_f32_32x32x16_bf16 v[80:95], v[202:205], v[122:125], v[80:95]
	ds_read_b128 v[198:201], v191 offset:29824
	ds_read_b128 v[202:205], v191 offset:36480
	s_waitcnt lgkmcnt(1)
	v_mfma_f32_32x32x16_bf16 v[96:111], v[198:201], v[118:121], v[96:111]
	s_waitcnt lgkmcnt(0)
	v_mfma_f32_32x32x16_bf16 v[80:95], v[202:205], v[118:121], v[80:95]
	ds_read_b128 v[198:201], v191 offset:29856
	ds_read_b128 v[202:205], v191 offset:36512
	s_waitcnt lgkmcnt(1)
	v_mfma_f32_32x32x16_bf16 v[96:111], v[198:201], v[114:117], v[96:111]
	v_exp_f32_e32 v198, v65
	v_exp_f32_e32 v199, v66
	v_exp_f32_e32 v200, v67
	v_exp_f32_e32 v201, v68
	v_cvt_pk_bf16_f32 v68, v161, v196
	s_waitcnt lgkmcnt(0)
	v_mfma_f32_32x32x16_bf16 v[80:95], v[202:205], v[114:117], v[80:95]
	v_exp_f32_e32 v202, v69
	v_exp_f32_e32 v203, v70
	v_exp_f32_e32 v204, v71
	v_exp_f32_e32 v205, v76
	v_cvt_pk_bf16_f32 v69, v158, v168
	v_cvt_pk_bf16_f32 v70, v159, v169
	v_cvt_pk_bf16_f32 v71, v160, v195
	v_cvt_pk_bf16_f32 v64, v150, v154
	v_cvt_pk_bf16_f32 v65, v151, v155
	v_cvt_pk_bf16_f32 v66, v152, v156
	v_cvt_pk_bf16_f32 v67, v153, v157
	v_cvt_pk_bf16_f32 v76, v197, v198
	v_cvt_pk_bf16_f32 v77, v199, v200
	v_cvt_pk_bf16_f32 v78, v201, v202
	v_cvt_pk_bf16_f32 v79, v203, v204
	v_cvt_pk_bf16_f32 v72, v72, v73
	v_cvt_pk_bf16_f32 v73, v74, v75
	v_cvt_pk_bf16_f32 v74, v205, v206
	v_cvt_pk_bf16_f32 v75, v207, v208
	v_lshl_add_u64 v[168:169], s[26:27], 0, v[164:165]
	s_mov_b32 s4, 0x218c0000
	v_add_co_u32_e32 v150, vcc, s4, v168
	s_nop 1
	v_addc_co_u32_e32 v151, vcc, 0, v169, vcc
	global_load_dwordx4 v[154:157], v[150:151], off offset:128
	global_load_dwordx4 v[158:161], v[150:151], off
	v_lshl_add_u64 v[150:151], s[26:27], 0, v[166:167]
	global_load_dwordx4 v[150:153], v[150:151], off
	ds_read_b64_tr_b16 v[196:197], v194 offset:0
	ds_read_b64_tr_b16 v[198:199], v194 offset:0x400
	ds_read_b64_tr_b16 v[200:201], v194 offset:0x800
	ds_read_b64_tr_b16 v[202:203], v194 offset:0xc00
	ds_read_b64_tr_b16 v[204:205], v194 offset:0x1000
	ds_read_b64_tr_b16 v[206:207], v194 offset:0x1400
	ds_read_b64_tr_b16 v[208:209], v194 offset:0x1800
	ds_read_b64_tr_b16 v[210:211], v194 offset:0x1c00
	s_waitcnt lgkmcnt(0)
	s_nop 0
	v_mfma_f32_32x32x16_bf16 v[0:15], v[68:71], v[196:199], v[0:15]
	ds_read_b64_tr_b16 v[196:197], v194 offset:0x200
	ds_read_b64_tr_b16 v[198:199], v194 offset:0x600
	v_exp_f32_e32 v195, v96
	v_exp_f32_e32 v212, v105
	v_mfma_f32_32x32x16_bf16 v[0:15], v[64:67], v[200:203], v[0:15]
	ds_read_b64_tr_b16 v[200:201], v194 offset:0xa00
	ds_read_b64_tr_b16 v[202:203], v194 offset:0xe00
	v_exp_f32_e32 v213, v106
	v_exp_f32_e32 v214, v107
	v_mfma_f32_32x32x16_bf16 v[0:15], v[76:79], v[204:207], v[0:15]
	ds_read_b64_tr_b16 v[204:205], v194 offset:0x1200
	ds_read_b64_tr_b16 v[206:207], v194 offset:0x1600
	v_exp_f32_e32 v215, v108
	v_exp_f32_e32 v216, v109
	v_mfma_f32_32x32x16_bf16 v[0:15], v[72:75], v[208:211], v[0:15]
	ds_read_b64_tr_b16 v[208:209], v194 offset:0x1a00
	ds_read_b64_tr_b16 v[210:211], v194 offset:0x1e00
	v_exp_f32_e32 v217, v110
	v_exp_f32_e32 v218, v111
	s_waitcnt lgkmcnt(0)
	v_mfma_f32_32x32x16_bf16 v[16:31], v[68:71], v[196:199], v[16:31]
	s_barrier
	s_waitcnt vmcnt(3)
	s_waitcnt vmcnt(5)
	ds_write_b128 v192, v[138:141]
	s_waitcnt vmcnt(4)
	ds_write_b128 v193, v[142:145] offset:16384
	v_mfma_f32_32x32x16_bf16 v[16:31], v[64:67], v[200:203], v[16:31]
	v_mfma_f32_32x32x16_bf16 v[16:31], v[76:79], v[204:207], v[16:31]
	v_mfma_f32_32x32x16_bf16 v[16:31], v[72:75], v[208:211], v[16:31]
	s_and_saveexec_b64 s[4:5], s[40:41]
	s_cbranch_execz .LBB0_1096
	s_waitcnt vmcnt(3)
	ds_write_b128 v112, v[146:149] offset:16512
; #define SBAR() __builtin_amdgcn_sched_barrier(0)
; #define SLOAD(i, k0) do { st_[i].vs = *reinterpret_cast<const bf16x8*>(&Vh[(size_t)((k0) + sr) * LDK + sc]); \
;     st_[i].ks = *reinterpret_cast<const bf16x8*>(&Kh[(size_t)((k0) + sr) * LDK + sc]); \
;     if (DQ == 96) st_[i].kr = *reinterpret_cast<const bf16x8*>(&Kr[(size_t)((k0) + sr2) * 32 + sc2]); } while (0)
; #define SWRITE(b, i) do { *(bf16x8*)(V_lds + (b) * SHM_V + vst0) = st_[i].vs; *(bf16x8*)(K_lds + (b) * SHM_K + kst0) = st_[i].ks; \
;     if (DQ == 96) { if (tid < 256) *(bf16x8*)(K_lds + (b) * SHM_K + kst2) = st_[i].kr; } } while (0)
; #define SWAIT() do { if (DQ == 96) asm volatile("s_waitcnt vmcnt(3)" ::: "memory"); else asm volatile("s_waitcnt vmcnt(2)" ::: "memory"); } while (0)
; #define SLOAD(i, k0) do { st_[i].vs = *reinterpret_cast<const bf16x8*>(&Vh[(size_t)((k0) + sr) * LDK + sc]); \
;     st_[i].ks = *reinterpret_cast<const bf16x8*>(&Kh[(size_t)((k0) + sr) * LDK + sc]); \
;     if (DQ == 96) st_[i].kr = *reinterpret_cast<const bf16x8*>(&Kr[(size_t)((k0) + sr2) * 32 + sc2]); } while (0)
; template <int DQ>
; __device__ __forceinline__ void qkt(f32x16& p0, f32x16& p1, const char* Ks, const bf16x8* qr, const f32x16& ci, int r32, int hi) {
;     constexpr int KROW = ACfg<DQ>::KROW;
; #pragma unroll
;     for (int d0 = 0; d0 < ACfg<DQ>::ND; ++d0) { const int cb = (d0 * 16 + hi * 8) * 2;
;         bf16x8 b0 = *reinterpret_cast<const bf16x8*>(Ks + r32 * KROW + cb);
;         bf16x8 b1 = *reinterpret_cast<const bf16x8*>(Ks + (32 + r32) * KROW + cb);
;         p0 = __builtin_amdgcn_mfma_f32_32x32x16_bf16(b0, qr[d0], d0 == 0 ? ci : p0, 0, 0, 0);
;         p1 = __builtin_amdgcn_mfma_f32_32x32x16_bf16(b1, qr[d0], d0 == 0 ? ci : p1, 0, 0, 0); }
; }
; template <int DQ, bool WIN, int LDQ, int LDK> ...
;     ...
;         lsum_upd();
;         if (WIN) win_mask(pB0, pB1, qrow - KBASE(j), hi);
;         exp16(pB0);
;         __syncthreads();
;         SBAR(); qkt<DQ>(pA0, pA1, K_lds, qr, minit, r32, hi);
;         finish(pB0, pB1); SBAR();
;         if (j + 3 < NT) SLOAD(SE, KBASE(j + 3)); SBAR();
;         pv(vb0 + SHM_V);
;         __syncthreads(); SWAIT(); SWRITE(1, SO);
;         lsum_upd();
;         if (WIN) win_mask(pA0, pA1, qrow - KBASE(j + 1), hi);
;         exp16(pA0);
;         __syncthreads();
;     }
.LBB0_1096:
	s_or_b64 exec, exec, s[4:5]
	s_add_i32 s17, s17, 2
	v_mfma_f32_16x16x32_bf16 v[32:35], v[68:71], v[36:39], v[32:35]
	v_exp_f32_e32 v204, v97
	v_exp_f32_e32 v205, v98
	v_exp_f32_e32 v206, v99
	v_exp_f32_e32 v207, v100
	v_exp_f32_e32 v208, v101
	v_exp_f32_e32 v209, v102
	v_exp_f32_e32 v210, v103
	v_mfma_f32_16x16x32_bf16 v[32:35], v[64:67], v[36:39], v[32:35]
	v_exp_f32_e32 v211, v104
	v_mfma_f32_16x16x32_bf16 v[32:35], v[76:79], v[36:39], v[32:35]
	s_waitcnt lgkmcnt(0)
	s_barrier
	v_mfma_f32_16x16x32_bf16 v[32:35], v[72:75], v[36:39], v[32:35]
	ds_read_b128 v[196:199], v191 offset:23040
	ds_read_b128 v[64:67], v191 offset:16384
	ds_read_b128 v[200:203], v191 offset:16416
	v_exp_f32_e32 v95, v95
	v_exp_f32_e32 v219, v88
	v_exp_f32_e32 v220, v89
	s_waitcnt lgkmcnt(1)
	v_mfma_f32_32x32x16_bf16 v[96:111], v[64:67], v[134:137], v[48:63]
	v_exp_f32_e32 v221, v90
	v_exp_f32_e32 v222, v91
	v_exp_f32_e32 v223, v92
	v_exp_f32_e32 v224, v93
	v_exp_f32_e32 v225, v94
	v_mfma_f32_32x32x16_bf16 v[64:79], v[196:199], v[134:137], v[48:63]
	ds_read_b128 v[196:199], v191 offset:23072
	s_waitcnt lgkmcnt(1)
	v_mfma_f32_32x32x16_bf16 v[96:111], v[200:203], v[130:133], v[96:111]
	s_waitcnt lgkmcnt(0)
	v_mfma_f32_32x32x16_bf16 v[64:79], v[196:199], v[130:133], v[64:79]
	ds_read_b128 v[196:199], v191 offset:16448
	ds_read_b128 v[200:203], v191 offset:23104
	s_waitcnt lgkmcnt(1)
	v_mfma_f32_32x32x16_bf16 v[96:111], v[196:199], v[126:129], v[96:111]
	s_waitcnt lgkmcnt(0)
	v_mfma_f32_32x32x16_bf16 v[64:79], v[200:203], v[126:129], v[64:79]
	ds_read_b128 v[196:199], v191 offset:16480
	ds_read_b128 v[200:203], v191 offset:23136
	s_waitcnt lgkmcnt(1)
	v_mfma_f32_32x32x16_bf16 v[96:111], v[196:199], v[122:125], v[96:111]
	s_waitcnt lgkmcnt(0)
	v_mfma_f32_32x32x16_bf16 v[64:79], v[200:203], v[122:125], v[64:79]
	ds_read_b128 v[196:199], v191 offset:16512
	ds_read_b128 v[200:203], v191 offset:23168
	s_waitcnt lgkmcnt(1)
	v_mfma_f32_32x32x16_bf16 v[96:111], v[196:199], v[118:121], v[96:111]
	s_waitcnt lgkmcnt(0)
	v_mfma_f32_32x32x16_bf16 v[64:79], v[200:203], v[118:121], v[64:79]
	ds_read_b128 v[196:199], v191 offset:16544
	ds_read_b128 v[200:203], v191 offset:23200
	s_waitcnt lgkmcnt(1)
	v_mfma_f32_32x32x16_bf16 v[96:111], v[196:199], v[114:117], v[96:111]
	v_exp_f32_e32 v196, v80
	v_exp_f32_e32 v197, v81
	v_exp_f32_e32 v198, v82
	v_exp_f32_e32 v199, v83
	v_cvt_pk_bf16_f32 v80, v195, v204
	v_cvt_pk_bf16_f32 v81, v205, v206
	v_cvt_pk_bf16_f32 v82, v207, v208
	s_waitcnt lgkmcnt(0)
	v_mfma_f32_32x32x16_bf16 v[64:79], v[200:203], v[114:117], v[64:79]
	v_exp_f32_e32 v200, v84
	v_exp_f32_e32 v201, v85
	v_exp_f32_e32 v202, v86
	v_exp_f32_e32 v203, v87
	v_cvt_pk_bf16_f32 v83, v209, v210
	v_cvt_pk_bf16_f32 v84, v211, v212
	v_cvt_pk_bf16_f32 v85, v213, v214
	v_cvt_pk_bf16_f32 v86, v215, v216
	v_cvt_pk_bf16_f32 v87, v217, v218
	v_cvt_pk_bf16_f32 v88, v196, v197
	v_cvt_pk_bf16_f32 v89, v198, v199
	v_cvt_pk_bf16_f32 v90, v200, v201
	v_cvt_pk_bf16_f32 v91, v202, v203
	v_cvt_pk_bf16_f32 v92, v219, v220
	v_cvt_pk_bf16_f32 v93, v221, v222
	v_cvt_pk_bf16_f32 v94, v223, v224
	v_cvt_pk_bf16_f32 v95, v225, v95
	s_cmpk_gt_u32 s17, 0x7c
	s_cselect_b64 s[4:5], -1, 0
	s_and_b64 vcc, exec, s[4:5]
	s_cbranch_vccnz .LBB0_1098
	v_add_co_u32_e32 v142, vcc, 0x21900000, v168
	s_waitcnt vmcnt(3)
	v_lshl_add_u64 v[146:147], s[26:27], 0, v[162:163]
	v_addc_co_u32_e32 v143, vcc, 0, v169, vcc
	global_load_dwordx4 v[138:141], v[142:143], off offset:128
	s_nop 0
	global_load_dwordx4 v[142:145], v[142:143], off
	s_nop 0
	global_load_dwordx4 v[146:149], v[146:147], off
